# P1 projection loop: first two counted waits of a unit that follows an epilogue leave the epilogue's 16 stores outstanding (vmcnt 24 instead of 8)
# baseline (speedup 1.0000x reference)
.LBB0_105:
	v_mov_b32_e32 v165, v27
	v_lshl_add_u64 v[58:59], s[86:87], 0, v[164:165]
	v_mov_b32_e32 v161, v27
	v_lshl_add_u64 v[84:85], s[86:87], 0, v[160:161]
	s_add_i32 m0, s17, 0x18000
	v_lshl_add_u64 v[58:59], v[58:59], 0, s[82:83]
	v_readlane_b32 s26, v251, 55
	v_mov_b32_e32 v167, v27
	s_waitcnt vmcnt(2)
	s_barrier
	global_load_lds_dwordx4 v[58:59], off
	v_lshl_add_u64 v[58:59], v[84:85], 0, s[82:83]
	s_add_i32 m0, s17, 0x1a000
	v_readlane_b32 s27, v251, 56
	s_add_i32 s22, s17, 0x8000
	v_mov_b32_e32 v163, v27
	global_load_lds_dwordx4 v[58:59], off
	v_lshl_add_u64 v[58:59], s[26:27], 0, v[166:167]
	s_mov_b32 m0, s22
	s_add_i32 s80, s17, 0xa000
	global_load_lds_dwordx4 v[58:59], off
	v_lshl_add_u64 v[58:59], s[26:27], 0, v[162:163]
	s_mov_b32 m0, s80
	s_and_b32 s1, s1, 3
	global_load_lds_dwordx4 v[58:59], off
	s_add_i32 m0, s17, 0x1c000
	v_lshl_add_u64 v[58:59], s[52:53], 0, v[164:165]
	global_load_lds_dwordx4 v[58:59], off
	v_lshl_add_u64 v[58:59], s[52:53], 0, v[160:161]
	s_add_i32 m0, s17, 0x1e000
	v_mul_lo_u32 v26, v26, s7
	global_load_lds_dwordx4 v[58:59], off
	v_bfe_u32 v59, v37, 4, 2
	v_and_b32_e32 v58, 15, v37
	v_lshlrev_b32_e32 v185, 4, v59
	v_lshlrev_b32_e32 v37, 2, v37
	v_lshl_or_b32 v184, s11, 6, v58
	v_lshl_or_b32 v58, v58, 6, v185
	s_lshl_b32 s11, s11, 13
	v_and_b32_e32 v37, 32, v37
	v_bitop3_b32 v84, v58, s11, v37 bitop3:0xde
	s_lshl_b32 s11, s1, 12
	v_bitop3_b32 v186, v58, s11, v37 bitop3:0xde
	s_cmpk_lt_u32 s0, 0x100
	v_lshrrev_b32_e32 v37, 1, v56
	v_mul_lo_u32 v58, v39, s7
	s_mov_b32 s11, 0x2c000
	s_cselect_b64 s[60:61], -1, 0
	v_cmp_eq_u32_e64 s[38:39], 0, v59
	s_lshl_b32 s26, s1, 1
	v_lshl_or_b32 v187, s1, 6, v185
	v_mad_u64_u32 v[58:59], s[0:1], v37, s11, v[58:59]
	v_and_b32_e32 v37, 1, v56
	v_lshl_or_b32 v37, v37, 6, v58
	v_lshl_add_u32 v176, v57, 1, v37
	v_lshrrev_b32_e32 v37, 1, v36
	v_mad_u64_u32 v[56:57], s[0:1], v37, s11, v[26:27]
	s_waitcnt vmcnt(6)
	v_and_b32_e32 v26, 1, v36
	v_readlane_b32 s0, v251, 36
	v_lshl_or_b32 v26, v26, 6, v56
	s_mov_b32 s94, s0
	v_readlane_b32 s0, v251, 34
	v_readlane_b32 s78, v251, 37
	s_mov_b32 s81, 0
	s_orn2_b32 s26, s26, 47
	v_mov_b32_e32 v177, v27
	v_lshl_add_u32 v178, v38, 1, v26
	v_mov_b32_e32 v179, v27
	v_add_u32_e32 v188, 0, v84
	v_readlane_b32 s31, v251, 35
	s_mov_b32 s30, s0
	s_mov_b64 s[76:77], s[86:87]
	v_readlane_b32 s79, v251, 38
	s_barrier
	s_mov_b32 s98, 0
	s_branch .LBB0_108

.LBB0_107:
	s_mov_b32 s98, 1
	s_andn2_b64 vcc, exec, s[0:1]
	s_mov_b32 s94, s27
	s_mov_b32 s31, s11
	s_mov_b32 s30, s92
	s_mov_b64 s[76:77], s[96:97]
	s_mov_b64 s[78:79], s[90:91]
	s_cbranch_vccz .LBB0_197

.LBB0_110:
	s_add_u32 vcc_lo, s78, 0x160080
	s_addc_u32 vcc_hi, s79, 0
	s_add_u32 s84, s76, 0x100
	s_addc_u32 s85, s77, 0
	s_mov_b32 s93, -2
	s_add_u32 s72, vcc_lo, 0xffea0080
	s_addc_u32 s73, vcc_hi, -1
	s_add_i32 s95, 0, 0x10000
	s_cmp_eq_u32 s93, 12
	s_cselect_b32 s79, s1, s73
	s_cselect_b32 s78, s0, s72
	v_add_u32_e32 v26, s95, v186
	s_cselect_b32 s77, s89, s85
	s_cselect_b32 s76, s88, s84
	s_add_i32 s12, 0, 0x14000
	ds_read_b128 v[36:39], v26
	ds_read_b128 v[56:59], v26 offset:1024
	ds_read_b128 v[84:87], v26 offset:2048
	ds_read_b128 v[104:107], v26 offset:3072
	v_add_u32_e32 v26, s12, v186
	ds_read_b128 v[124:127], v26
	ds_read_b128 v[144:147], v26 offset:1024
	ds_read_b128 v[156:159], v26 offset:2048
	ds_read_b128 v[180:183], v26 offset:3072
	v_lshl_add_u64 v[226:227], vcc, 0, v[176:177]
	s_add_i32 m0, s17, 0xc000
	ds_read_b128 v[190:193], v188
	ds_read_b128 v[194:197], v188 offset:1024
	ds_read_b128 v[198:201], v188 offset:2048
	ds_read_b128 v[202:205], v188 offset:3072
	ds_read_b128 v[206:209], v188 offset:4096
	ds_read_b128 v[210:213], v188 offset:5120
	ds_read_b128 v[214:217], v188 offset:6144
	ds_read_b128 v[218:221], v188 offset:7168
	global_load_lds_dwordx4 v[226:227], off
	v_lshl_add_u64 v[226:227], vcc, 0, v[178:179]
	s_add_i32 m0, s17, 0xe000
	s_nop 0
	global_load_lds_dwordx4 v[226:227], off
	s_cmp_eq_u32 s98, 0
	s_cbranch_scc1 .Lrw_strict_a
	s_waitcnt vmcnt(24)
	s_branch .Lrw_done_a
.Lrw_strict_a:
	s_waitcnt vmcnt(8)
.Lrw_done_a:
	s_waitcnt lgkmcnt(0)
	s_setprio 1
	s_barrier
	v_mfma_f32_16x16x32_bf16 v[148:151], v[36:39], v[190:193], 0
	v_mfma_f32_16x16x32_bf16 v[152:155], v[84:87], v[190:193], 0
	v_mfma_f32_16x16x32_bf16 v[128:131], v[36:39], v[198:201], 0
	v_mfma_f32_16x16x32_bf16 v[132:135], v[84:87], v[198:201], 0
	v_mfma_f32_16x16x32_bf16 v[108:111], v[36:39], v[206:209], 0
	v_mfma_f32_16x16x32_bf16 v[112:115], v[84:87], v[206:209], 0
	v_mfma_f32_16x16x32_bf16 v[88:91], v[36:39], v[214:217], 0
	v_mfma_f32_16x16x32_bf16 v[92:95], v[84:87], v[214:217], 0
	v_mfma_f32_16x16x32_bf16 v[148:151], v[56:59], v[194:197], v[148:151]
	v_mfma_f32_16x16x32_bf16 v[152:155], v[104:107], v[194:197], v[152:155]
	v_mfma_f32_16x16x32_bf16 v[128:131], v[56:59], v[202:205], v[128:131]
	v_mfma_f32_16x16x32_bf16 v[132:135], v[104:107], v[202:205], v[132:135]
	v_mfma_f32_16x16x32_bf16 v[108:111], v[56:59], v[210:213], v[108:111]
	v_mfma_f32_16x16x32_bf16 v[112:115], v[104:107], v[210:213], v[112:115]
	v_mfma_f32_16x16x32_bf16 v[88:91], v[56:59], v[218:221], v[88:91]
	v_mfma_f32_16x16x32_bf16 v[92:95], v[104:107], v[218:221], v[92:95]
	s_setprio 0
	s_setprio 1
	v_mfma_f32_16x16x32_bf16 v[140:143], v[124:127], v[190:193], 0
	v_mfma_f32_16x16x32_bf16 v[136:139], v[156:159], v[190:193], 0
	v_mfma_f32_16x16x32_bf16 v[120:123], v[124:127], v[198:201], 0
	v_mfma_f32_16x16x32_bf16 v[116:119], v[156:159], v[198:201], 0
	v_mfma_f32_16x16x32_bf16 v[100:103], v[124:127], v[206:209], 0
	v_mfma_f32_16x16x32_bf16 v[96:99], v[156:159], v[206:209], 0
	v_mfma_f32_16x16x32_bf16 v[80:83], v[124:127], v[214:217], 0
	v_mfma_f32_16x16x32_bf16 v[76:79], v[156:159], v[214:217], 0
	v_mfma_f32_16x16x32_bf16 v[140:143], v[144:147], v[194:197], v[140:143]
	v_mfma_f32_16x16x32_bf16 v[136:139], v[180:183], v[194:197], v[136:139]
	v_mfma_f32_16x16x32_bf16 v[120:123], v[144:147], v[202:205], v[120:123]
	v_mfma_f32_16x16x32_bf16 v[116:119], v[180:183], v[202:205], v[116:119]
	v_mfma_f32_16x16x32_bf16 v[100:103], v[144:147], v[210:213], v[100:103]
	v_mfma_f32_16x16x32_bf16 v[96:99], v[180:183], v[210:213], v[96:99]
	v_mfma_f32_16x16x32_bf16 v[80:83], v[144:147], v[218:221], v[80:83]
	v_mfma_f32_16x16x32_bf16 v[76:79], v[180:183], v[218:221], v[76:79]
	s_barrier
	s_setprio 0
	s_add_i32 s72, s95, s16
	v_lshl_add_u64 v[226:227], s[76:77], 0, v[164:165]
	s_mov_b32 m0, s72
	ds_read_b128 v[190:193], v188 offset:16384
	ds_read_b128 v[194:197], v188 offset:17408
	ds_read_b128 v[198:201], v188 offset:18432
	ds_read_b128 v[202:205], v188 offset:19456
	ds_read_b128 v[206:209], v188 offset:20480
	ds_read_b128 v[210:213], v188 offset:21504
	ds_read_b128 v[214:217], v188 offset:22528
	ds_read_b128 v[218:221], v188 offset:23552
	global_load_lds_dwordx4 v[226:227], off
	s_add_i32 m0, s72, 0x2000
	s_add_u32 s72, s76, 0x40000
	v_lshl_add_u64 v[228:229], s[76:77], 0, v[160:161]
	s_addc_u32 s73, s77, 0
	s_add_i32 s12, s12, s16
	global_load_lds_dwordx4 v[228:229], off
	v_lshl_add_u64 v[230:231], s[72:73], 0, v[164:165]
	s_mov_b32 m0, s12
	v_lshl_add_u64 v[232:233], s[78:79], 0, v[162:163]
	global_load_lds_dwordx4 v[230:231], off
	v_lshl_add_u64 v[230:231], s[72:73], 0, v[160:161]
	s_add_i32 m0, s12, 0x2000
	s_nop 0
	global_load_lds_dwordx4 v[230:231], off
	v_lshl_add_u64 v[230:231], s[78:79], 0, v[166:167]
	s_mov_b32 m0, s17
	s_nop 0
	global_load_lds_dwordx4 v[230:231], off
	s_mov_b32 m0, s46
	s_nop 0
	global_load_lds_dwordx4 v[232:233], off
	s_cmp_eq_u32 s98, 0
	s_cbranch_scc1 .Lrw_strict_b
	s_waitcnt vmcnt(24)
	s_branch .Lrw_done_b

.Lrw_done_b:
	s_waitcnt lgkmcnt(0)
	s_setprio 1
	s_barrier
	v_mfma_f32_16x16x32_bf16 v[68:71], v[36:39], v[190:193], 0
	v_mfma_f32_16x16x32_bf16 v[72:75], v[84:87], v[190:193], 0
	v_mfma_f32_16x16x32_bf16 v[48:51], v[36:39], v[198:201], 0
	v_mfma_f32_16x16x32_bf16 v[52:55], v[84:87], v[198:201], 0
	v_mfma_f32_16x16x32_bf16 v[28:31], v[36:39], v[206:209], 0
	v_mfma_f32_16x16x32_bf16 v[32:35], v[84:87], v[206:209], 0
	v_mfma_f32_16x16x32_bf16 v[10:13], v[36:39], v[214:217], 0
	v_mfma_f32_16x16x32_bf16 v[14:17], v[84:87], v[214:217], 0
	v_mfma_f32_16x16x32_bf16 v[68:71], v[56:59], v[194:197], v[68:71]
	v_mfma_f32_16x16x32_bf16 v[72:75], v[104:107], v[194:197], v[72:75]
	v_mfma_f32_16x16x32_bf16 v[48:51], v[56:59], v[202:205], v[48:51]
	v_mfma_f32_16x16x32_bf16 v[52:55], v[104:107], v[202:205], v[52:55]
	v_mfma_f32_16x16x32_bf16 v[28:31], v[56:59], v[210:213], v[28:31]
	v_mfma_f32_16x16x32_bf16 v[32:35], v[104:107], v[210:213], v[32:35]
	v_mfma_f32_16x16x32_bf16 v[10:13], v[56:59], v[218:221], v[10:13]
	v_mfma_f32_16x16x32_bf16 v[14:17], v[104:107], v[218:221], v[14:17]
	s_setprio 0
	s_setprio 1
	v_mfma_f32_16x16x32_bf16 v[44:47], v[124:127], v[198:201], 0
	v_mfma_f32_16x16x32_bf16 v[40:43], v[156:159], v[198:201], 0
	v_mfma_f32_16x16x32_bf16 v[22:25], v[124:127], v[206:209], 0
	v_mfma_f32_16x16x32_bf16 v[18:21], v[156:159], v[206:209], 0
	v_mfma_f32_16x16x32_bf16 v[2:5], v[124:127], v[214:217], 0
	v_mfma_f32_16x16x32_bf16 v[6:9], v[156:159], v[214:217], 0
	v_mfma_f32_16x16x32_bf16 v[36:39], v[124:127], v[190:193], 0
	v_mfma_f32_16x16x32_bf16 v[56:59], v[156:159], v[190:193], 0
	v_mfma_f32_16x16x32_bf16 v[44:47], v[144:147], v[202:205], v[44:47]
	v_mfma_f32_16x16x32_bf16 v[40:43], v[180:183], v[202:205], v[40:43]
	v_mfma_f32_16x16x32_bf16 v[22:25], v[144:147], v[210:213], v[22:25]
	v_mfma_f32_16x16x32_bf16 v[18:21], v[180:183], v[210:213], v[18:21]
	v_mfma_f32_16x16x32_bf16 v[2:5], v[144:147], v[218:221], v[2:5]
	v_mfma_f32_16x16x32_bf16 v[6:9], v[180:183], v[218:221], v[6:9]
	v_mfma_f32_16x16x32_bf16 v[36:39], v[144:147], v[194:197], v[36:39]
	v_mfma_f32_16x16x32_bf16 v[56:59], v[180:183], v[194:197], v[56:59]
	s_barrier
	s_setprio 0
	s_add_i32 s12, 0, 0x18000
	v_add_u32_e32 v26, s12, v186
	s_add_i32 s95, 0, 0x1c000
	ds_read_b128 v[60:63], v26
	ds_read_b128 v[64:67], v26 offset:1024
	ds_read_b128 v[84:87], v26 offset:2048
	ds_read_b128 v[104:107], v26 offset:3072
	v_add_u32_e32 v26, s95, v186
	ds_read_b128 v[124:127], v26
	ds_read_b128 v[144:147], v26 offset:1024
	ds_read_b128 v[156:159], v26 offset:2048
	ds_read_b128 v[180:183], v26 offset:3072
	s_add_u32 s72, s78, 0x160000
	s_addc_u32 s73, s79, 0
	s_mov_b32 m0, s47
	v_lshl_add_u64 v[234:235], s[72:73], 0, v[166:167]
	ds_read_b128 v[190:193], v188 offset:32768
	ds_read_b128 v[194:197], v188 offset:33792
	ds_read_b128 v[198:201], v188 offset:34816
	ds_read_b128 v[202:205], v188 offset:35840
	ds_read_b128 v[206:209], v188 offset:36864
	ds_read_b128 v[210:213], v188 offset:37888
	ds_read_b128 v[214:217], v188 offset:38912
	ds_read_b128 v[218:221], v188 offset:39936
	global_load_lds_dwordx4 v[234:235], off
	v_lshl_add_u64 v[234:235], s[72:73], 0, v[162:163]
	s_mov_b32 m0, s8
	s_nop 0
	global_load_lds_dwordx4 v[234:235], off
	s_waitcnt vmcnt(8)
	s_waitcnt lgkmcnt(0)
	s_setprio 1
	s_barrier
	v_mfma_f32_16x16x32_bf16 v[148:151], v[60:63], v[190:193], v[148:151]
	v_mfma_f32_16x16x32_bf16 v[152:155], v[84:87], v[190:193], v[152:155]
	v_mfma_f32_16x16x32_bf16 v[128:131], v[60:63], v[198:201], v[128:131]
	v_mfma_f32_16x16x32_bf16 v[132:135], v[84:87], v[198:201], v[132:135]
	v_mfma_f32_16x16x32_bf16 v[108:111], v[60:63], v[206:209], v[108:111]
	v_mfma_f32_16x16x32_bf16 v[112:115], v[84:87], v[206:209], v[112:115]
	v_mfma_f32_16x16x32_bf16 v[88:91], v[60:63], v[214:217], v[88:91]
	v_mfma_f32_16x16x32_bf16 v[92:95], v[84:87], v[214:217], v[92:95]
	v_mfma_f32_16x16x32_bf16 v[148:151], v[64:67], v[194:197], v[148:151]
	v_mfma_f32_16x16x32_bf16 v[152:155], v[104:107], v[194:197], v[152:155]
	v_mfma_f32_16x16x32_bf16 v[128:131], v[64:67], v[202:205], v[128:131]
	v_mfma_f32_16x16x32_bf16 v[132:135], v[104:107], v[202:205], v[132:135]
	v_mfma_f32_16x16x32_bf16 v[108:111], v[64:67], v[210:213], v[108:111]
	v_mfma_f32_16x16x32_bf16 v[112:115], v[104:107], v[210:213], v[112:115]
	v_mfma_f32_16x16x32_bf16 v[88:91], v[64:67], v[218:221], v[88:91]
	v_mfma_f32_16x16x32_bf16 v[92:95], v[104:107], v[218:221], v[92:95]
	s_setprio 0
	s_setprio 1
	v_mfma_f32_16x16x32_bf16 v[140:143], v[124:127], v[190:193], v[140:143]
	v_mfma_f32_16x16x32_bf16 v[136:139], v[156:159], v[190:193], v[136:139]
	v_mfma_f32_16x16x32_bf16 v[120:123], v[124:127], v[198:201], v[120:123]
	v_mfma_f32_16x16x32_bf16 v[116:119], v[156:159], v[198:201], v[116:119]
	v_mfma_f32_16x16x32_bf16 v[100:103], v[124:127], v[206:209], v[100:103]
	v_mfma_f32_16x16x32_bf16 v[96:99], v[156:159], v[206:209], v[96:99]
	v_mfma_f32_16x16x32_bf16 v[80:83], v[124:127], v[214:217], v[80:83]
	v_mfma_f32_16x16x32_bf16 v[76:79], v[156:159], v[214:217], v[76:79]
	v_mfma_f32_16x16x32_bf16 v[140:143], v[144:147], v[194:197], v[140:143]
	v_mfma_f32_16x16x32_bf16 v[136:139], v[180:183], v[194:197], v[136:139]
	v_mfma_f32_16x16x32_bf16 v[120:123], v[144:147], v[202:205], v[120:123]
	v_mfma_f32_16x16x32_bf16 v[116:119], v[180:183], v[202:205], v[116:119]
	v_mfma_f32_16x16x32_bf16 v[100:103], v[144:147], v[210:213], v[100:103]
	v_mfma_f32_16x16x32_bf16 v[96:99], v[180:183], v[210:213], v[96:99]
	v_mfma_f32_16x16x32_bf16 v[80:83], v[144:147], v[218:221], v[80:83]
	v_mfma_f32_16x16x32_bf16 v[76:79], v[180:183], v[218:221], v[76:79]
	s_barrier
	s_setprio 0
	s_add_i32 s12, s12, s16
	v_lshl_add_u64 v[226:227], v[226:227], 0, s[82:83]
	s_mov_b32 m0, s12
	ds_read_b128 v[190:193], v188 offset:49152
	ds_read_b128 v[194:197], v188 offset:50176
	ds_read_b128 v[198:201], v188 offset:51200
	ds_read_b128 v[202:205], v188 offset:52224
	ds_read_b128 v[206:209], v188 offset:53248
	ds_read_b128 v[210:213], v188 offset:54272
	ds_read_b128 v[214:217], v188 offset:55296
	ds_read_b128 v[218:221], v188 offset:56320
	global_load_lds_dwordx4 v[226:227], off
	s_add_i32 m0, s12, 0x2000
	s_add_u32 s72, s76, 0x40080
	v_lshl_add_u64 v[226:227], v[228:229], 0, s[82:83]
	s_addc_u32 s73, s77, 0
	s_add_i32 s12, s95, s16
	global_load_lds_dwordx4 v[226:227], off
	v_lshl_add_u64 v[226:227], s[72:73], 0, v[164:165]
	s_mov_b32 m0, s12
	s_nop 0
	global_load_lds_dwordx4 v[226:227], off
	v_lshl_add_u64 v[226:227], s[72:73], 0, v[160:161]
	s_add_i32 m0, s12, 0x2000
	s_nop 0
	global_load_lds_dwordx4 v[226:227], off
	v_lshl_add_u64 v[226:227], v[230:231], 0, s[82:83]
	s_mov_b32 m0, s22
	s_nop 0
	global_load_lds_dwordx4 v[226:227], off
	v_lshl_add_u64 v[226:227], v[232:233], 0, s[82:83]
	s_mov_b32 m0, s80
	s_nop 0
	global_load_lds_dwordx4 v[226:227], off
	s_waitcnt vmcnt(8)
	s_waitcnt lgkmcnt(0)
	s_setprio 1
	s_barrier
	v_mfma_f32_16x16x32_bf16 v[68:71], v[60:63], v[190:193], v[68:71]
	v_mfma_f32_16x16x32_bf16 v[72:75], v[84:87], v[190:193], v[72:75]
	v_mfma_f32_16x16x32_bf16 v[48:51], v[60:63], v[198:201], v[48:51]
	v_mfma_f32_16x16x32_bf16 v[52:55], v[84:87], v[198:201], v[52:55]
	v_mfma_f32_16x16x32_bf16 v[28:31], v[60:63], v[206:209], v[28:31]
	v_mfma_f32_16x16x32_bf16 v[32:35], v[84:87], v[206:209], v[32:35]
	v_mfma_f32_16x16x32_bf16 v[10:13], v[60:63], v[214:217], v[10:13]
	v_mfma_f32_16x16x32_bf16 v[14:17], v[84:87], v[214:217], v[14:17]
	v_mfma_f32_16x16x32_bf16 v[68:71], v[64:67], v[194:197], v[68:71]
	v_mfma_f32_16x16x32_bf16 v[72:75], v[104:107], v[194:197], v[72:75]
	v_mfma_f32_16x16x32_bf16 v[48:51], v[64:67], v[202:205], v[48:51]
	v_mfma_f32_16x16x32_bf16 v[52:55], v[104:107], v[202:205], v[52:55]
	v_mfma_f32_16x16x32_bf16 v[28:31], v[64:67], v[210:213], v[28:31]
	v_mfma_f32_16x16x32_bf16 v[32:35], v[104:107], v[210:213], v[32:35]
	v_mfma_f32_16x16x32_bf16 v[10:13], v[64:67], v[218:221], v[10:13]
	v_mfma_f32_16x16x32_bf16 v[14:17], v[104:107], v[218:221], v[14:17]
	s_setprio 0
	s_setprio 1
	v_mfma_f32_16x16x32_bf16 v[36:39], v[124:127], v[190:193], v[36:39]
	v_mfma_f32_16x16x32_bf16 v[64:67], v[144:147], v[194:197], v[36:39]
	v_mfma_f32_16x16x32_bf16 v[36:39], v[156:159], v[190:193], v[56:59]
	v_mfma_f32_16x16x32_bf16 v[60:63], v[180:183], v[194:197], v[36:39]
	v_mfma_f32_16x16x32_bf16 v[36:39], v[124:127], v[198:201], v[44:47]
	v_mfma_f32_16x16x32_bf16 v[44:47], v[144:147], v[202:205], v[36:39]
	v_mfma_f32_16x16x32_bf16 v[36:39], v[156:159], v[198:201], v[40:43]
	v_mfma_f32_16x16x32_bf16 v[22:25], v[124:127], v[206:209], v[22:25]
	v_mfma_f32_16x16x32_bf16 v[18:21], v[156:159], v[206:209], v[18:21]
	v_mfma_f32_16x16x32_bf16 v[2:5], v[124:127], v[214:217], v[2:5]
	v_mfma_f32_16x16x32_bf16 v[6:9], v[156:159], v[214:217], v[6:9]
	v_mfma_f32_16x16x32_bf16 v[40:43], v[180:183], v[202:205], v[36:39]
	v_mfma_f32_16x16x32_bf16 v[22:25], v[144:147], v[210:213], v[22:25]
	v_mfma_f32_16x16x32_bf16 v[18:21], v[180:183], v[210:213], v[18:21]
	v_mfma_f32_16x16x32_bf16 v[2:5], v[144:147], v[218:221], v[2:5]
	v_mfma_f32_16x16x32_bf16 v[6:9], v[180:183], v[218:221], v[6:9]
	s_barrier
	s_setprio 0
	s_add_i32 s93, s93, 2
	s_add_u32 vcc_lo, vcc_lo, 0x100
	s_addc_u32 vcc_hi, vcc_hi, 0
	s_add_u32 s84, s84, 0x100
	s_addc_u32 s85, s85, 0
